# attention unit epilogues store 16-byte pieces (v_permlane32_swap pairs, half the store instructions) on top of SGU load hoist
# baseline (speedup 1.0000x reference)
; DI unsigned pk2(float lo, float hi) { typedef float v2f __attribute__((ext_vector_type(2))); typedef __bf16 v2b __attribute__((ext_vector_type(2))); v2f v = {lo, hi}; v2b b = __builtin_convertvector(v, v2b); return __builtin_bit_cast(unsigned, b); }
; DI float xhalf_sum(float m) { auto rr = __builtin_amdgcn_permlane32_swap(__float_as_uint(m), __float_as_uint(m), false, false); return __uint_as_float(rr[0]) + __uint_as_float(rr[1]); }
; template <int DQK, int DV, bool CAUSAL, int KT, bool PRIO>
; DI void attn_unit(const bf16_t* Qb, int qpitch, const bf16_t* Kb, int kpitch, const bf16_t* Vtb, int vpitch, bf16_t* Ob, int opitch, int q0, int nt, LAS unsigned char* lds, float kbound, const float* qgain, const int* qpos, float qscale) {
;     ...
;     lrun = xhalf_sum(lrun);
;     const float inv = 1.0f / lrun;
;     bf16_t* orow = Ob + (size_t)(32 * w + r) * opitch;
; #pragma unroll
;     for (int d = 0; d < DV / 32; ++d)
; #pragma unroll
;         for (int g = 0; g < 4; ++g) { u32x2 wv; wv.x = pk2(o[d][4 * g] * inv, o[d][4 * g + 1] * inv); wv.y = pk2(o[d][4 * g + 2] * inv, o[d][4 * g + 3] * inv);
;             *(u32x2*)(orow + 32 * d + 8 * g + 4 * h) = wv; }
.LBB0_1479:
	v_mov_b32_e32 v2, v0
	s_nop 1
	v_permlane32_swap_b32_e32 v0, v2
	v_add_f32_e32 v0, v0, v2
	v_div_scale_f32 v2, s[2:3], v0, v0, 1.0
	v_rcp_f32_e32 v3, v2
	s_lshl_b64 s[2:3], s[26:27], 10
	s_add_u32 s2, s65, s2
	s_addc_u32 s3, s66, s3
	v_fma_f32 v4, -v2, v3, 1.0
	v_fmac_f32_e32 v3, v4, v3
	v_div_scale_f32 v4, vcc, 1.0, v0, 1.0
	v_mul_f32_e32 v5, v4, v3
	v_fma_f32 v6, -v2, v5, v4
	v_fmac_f32_e32 v5, v6, v3
	v_fma_f32 v2, -v2, v5, v4
	v_div_fmas_f32 v2, v2, v3, v5
	v_div_fixup_f32 v2, v2, v0, 1.0
	v_lshlrev_b64 v[4:5], 10, v[162:163]
	v_lshl_add_u64 v[4:5], s[2:3], 0, v[4:5]
	v_lshlrev_b32_e32 v0, 2, v180
	v_lshl_add_u64 v[4:5], v[4:5], 0, v[0:1]
	v_pk_mul_f32 v[6:7], v[32:33], v[2:3] op_sel_hi:[1,0]
	v_pk_mul_f32 v[8:9], v[34:35], v[2:3] op_sel_hi:[1,0]
	v_cvt_pk_bf16_f32 v6, v6, v7
	v_cvt_pk_bf16_f32 v7, v8, v9
	v_pk_mul_f32 v[8:9], v[36:37], v[2:3] op_sel_hi:[1,0]
	v_pk_mul_f32 v[10:11], v[38:39], v[2:3] op_sel_hi:[1,0]
	v_cvt_pk_bf16_f32 v8, v8, v9
	v_cvt_pk_bf16_f32 v9, v10, v11
	s_nop 1
	v_permlane32_swap_b32_e32 v6, v8
	v_permlane32_swap_b32_e32 v7, v9
	flat_store_dwordx4 v[4:5], v[6:9]
	v_pk_mul_f32 v[10:11], v[40:41], v[2:3] op_sel_hi:[1,0]
	v_pk_mul_f32 v[12:13], v[42:43], v[2:3] op_sel_hi:[1,0]
	v_cvt_pk_bf16_f32 v10, v10, v11
	v_cvt_pk_bf16_f32 v11, v12, v13
	v_pk_mul_f32 v[12:13], v[44:45], v[2:3] op_sel_hi:[1,0]
	v_pk_mul_f32 v[14:15], v[46:47], v[2:3] op_sel_hi:[1,0]
	v_cvt_pk_bf16_f32 v12, v12, v13
	v_cvt_pk_bf16_f32 v13, v14, v15
	s_nop 1
	v_permlane32_swap_b32_e32 v10, v12
	v_permlane32_swap_b32_e32 v11, v13
	flat_store_dwordx4 v[4:5], v[10:13] offset:32
	v_pk_mul_f32 v[6:7], v[16:17], v[2:3] op_sel_hi:[1,0]
	v_pk_mul_f32 v[8:9], v[18:19], v[2:3] op_sel_hi:[1,0]
	v_cvt_pk_bf16_f32 v6, v6, v7
	v_cvt_pk_bf16_f32 v7, v8, v9
	v_pk_mul_f32 v[8:9], v[20:21], v[2:3] op_sel_hi:[1,0]
	v_pk_mul_f32 v[14:15], v[22:23], v[2:3] op_sel_hi:[1,0]
	v_cvt_pk_bf16_f32 v8, v8, v9
	v_cvt_pk_bf16_f32 v9, v14, v15
	s_nop 1
	v_permlane32_swap_b32_e32 v6, v8
	v_permlane32_swap_b32_e32 v7, v9
	flat_store_dwordx4 v[4:5], v[6:9] offset:64
	v_pk_mul_f32 v[10:11], v[24:25], v[2:3] op_sel_hi:[1,0]
	v_pk_mul_f32 v[12:13], v[26:27], v[2:3] op_sel_hi:[1,0]
	v_cvt_pk_bf16_f32 v10, v10, v11
	v_cvt_pk_bf16_f32 v11, v12, v13
	v_pk_mul_f32 v[12:13], v[28:29], v[2:3] op_sel_hi:[1,0]
	v_pk_mul_f32 v[14:15], v[30:31], v[2:3] op_sel_hi:[1,0]
	v_cvt_pk_bf16_f32 v12, v12, v13
	v_cvt_pk_bf16_f32 v13, v14, v15
	s_nop 1
	v_permlane32_swap_b32_e32 v10, v12
	v_permlane32_swap_b32_e32 v11, v13
	s_mov_b64 s[2:3], 0
	s_and_b64 vcc, exec, s[34:35]
	flat_store_dwordx4 v[4:5], v[10:13] offset:96
	s_cbranch_vccnz .LBB0_1477

; #define LAS __attribute__((address_space(3)))
; DI unsigned pk2(float lo, float hi) { typedef float v2f __attribute__((ext_vector_type(2))); typedef __bf16 v2b __attribute__((ext_vector_type(2))); v2f v = {lo, hi}; v2b b = __builtin_convertvector(v, v2b); return __builtin_bit_cast(unsigned, b); }
; template <int DQK, int DV, bool CAUSAL, int KT, bool PRIO>
; DI void attn_unit(const bf16_t* Qb, int qpitch, const bf16_t* Kb, int kpitch, const bf16_t* Vtb, int vpitch, bf16_t* Ob, int opitch, int q0, int nt, LAS unsigned char* lds, float kbound, const float* qgain, const int* qpos, float qscale) {
;     ...
;                     const LAS unsigned char* vb = lds + VOFF + buf * VBUF + r * VS + h * 8 + 128 * hf;
;                     float ps = 0.f;
; #pragma unroll
;                     for (int kb2 = 0; kb2 < 2; ++kb2) {
;                         f32x16& sx = kb2 == 0 ? s0 : s1;
; #pragma unroll
;                         for (int i = 0; i < 16; ++i) { sx[i] = __builtin_amdgcn_exp2f(sx[i]); ps += sx[i]; }
;                         if (PRIO) __builtin_amdgcn_s_setprio(1);
; #pragma unroll
;                         for (int sf = 0; sf < 2; ++sf) {
;                             u32x4 pw; pw.x = pk2(sx[8 * sf], sx[8 * sf + 1]); pw.y = pk2(sx[8 * sf + 2], sx[8 * sf + 3]); pw.z = pk2(sx[8 * sf + 4], sx[8 * sf + 5]); pw.w = pk2(sx[8 * sf + 6], sx[8 * sf + 7]);
;                             const bf16x8 pf = __builtin_bit_cast(bf16x8, pw);
; #pragma unroll
;                             for (int d = 0; d < DV / 32; ++d) {
;                                 const LAS unsigned char* vp = vb + d * 32 * VS + (32 * kb2 + 16 * sf) * 2;
;                                 const s16x4 lo = *(const LAS s16x4*)vp, hi = *(const LAS s16x4*)(vp + 16);
;                                 const bf16x8 a = (bf16x8){lo[0], lo[1], lo[2], lo[3], hi[0], hi[1], hi[2], hi[3]};
;                                 o[d] = MFMA32(a, pf, o[d]);
;                                 if (!PRIO) asm volatile("" ::: "memory");
;                             }
;                         }
;                         if (PRIO) __builtin_amdgcn_s_setprio(0);
;                     }
;                     lrun += ps;
;                 }
;             }
;         }
;         if (kt + 1 < nt) lstore(buf ^ 1);
;         __syncthreads();
;     }
;     lrun = xhalf_sum(lrun);
;     const float inv = 1.0f / lrun;
.LBB0_1519:
	ds_read2_b64 v[88:91], v97 offset0:128 offset1:130
	v_exp_f32_e32 v96, v104
	v_exp_f32_e32 v104, v105
	v_exp_f32_e32 v105, v106
	v_exp_f32_e32 v106, v107
	v_exp_f32_e32 v107, v100
	v_exp_f32_e32 v109, v101
	v_exp_f32_e32 v110, v102
	v_exp_f32_e32 v111, v103
	v_cvt_pk_bf16_f32 v92, v96, v104
	v_cvt_pk_bf16_f32 v93, v105, v106
	v_cvt_pk_bf16_f32 v94, v107, v109
	v_cvt_pk_bf16_f32 v95, v110, v111
	v_exp_f32_e32 v113, v75
	v_exp_f32_e32 v114, v76
	s_waitcnt lgkmcnt(0)
	v_mfma_f32_32x32x16_bf16 v[48:63], v[88:91], v[92:95], v[48:63]
	ds_read2_b64 v[88:91], v170 offset0:160 offset1:162
	v_exp_f32_e32 v115, v77
	v_exp_f32_e32 v112, v86
	v_exp_f32_e32 v84, v84
	v_exp_f32_e32 v85, v85
	v_exp_f32_e32 v116, v68
	s_waitcnt lgkmcnt(0)
	v_mfma_f32_32x32x16_bf16 v[32:47], v[88:91], v[92:95], v[32:47]
	ds_read2_b64 v[88:91], v208 offset0:192 offset1:194
	ds_read2_b64 v[100:103], v209 offset0:224 offset1:226
	v_exp_f32_e32 v117, v69
	v_add_f32_e32 v96, 0, v96
	v_add_f32_e32 v96, v104, v96
	s_waitcnt lgkmcnt(1)
	v_mfma_f32_32x32x16_bf16 v[16:31], v[88:91], v[92:95], v[16:31]
	v_exp_f32_e32 v91, v74
	ds_read2_b64 v[74:77], v97 offset0:132 offset1:134
	v_exp_f32_e32 v90, v87
	v_cvt_pk_bf16_f32 v88, v114, v115
	v_cvt_pk_bf16_f32 v87, v91, v113
	v_cvt_pk_bf16_f32 v86, v112, v90
	s_waitcnt lgkmcnt(1)
	v_mfma_f32_32x32x16_bf16 v[0:15], v[100:103], v[92:95], v[0:15]
	v_exp_f32_e32 v92, v72
	v_exp_f32_e32 v93, v73
	v_exp_f32_e32 v94, v98
	v_exp_f32_e32 v95, v99
	v_exp_f32_e32 v98, v82
	v_cvt_pk_bf16_f32 v89, v92, v93
	v_exp_f32_e32 v99, v83
	v_exp_f32_e32 v100, v80
	s_waitcnt lgkmcnt(0)
	v_mfma_f32_32x32x16_bf16 v[48:63], v[74:77], v[86:89], v[48:63]
	ds_read2_b64 v[72:75], v170 offset0:164 offset1:166
	ds_read2_b64 v[76:79], v208 offset0:196 offset1:198
	v_exp_f32_e32 v102, v64
	v_exp_f32_e32 v103, v65
	v_exp_f32_e32 v101, v71
	s_waitcnt lgkmcnt(1)
	v_mfma_f32_32x32x16_bf16 v[32:47], v[72:75], v[86:89], v[32:47]
	ds_read2_b64 v[72:75], v209 offset0:228 offset1:230
	v_cvt_pk_bf16_f32 v71, v116, v117
	s_lshl_b64 s[4:5], s[4:5], 9
	s_lshl_b32 s6, s35, 7
	s_lshl_b64 s[4:5], s[4:5], 1
	s_add_u32 s4, s16, s4
	s_waitcnt lgkmcnt(1)
	v_mfma_f32_32x32x16_bf16 v[16:31], v[76:79], v[86:89], v[16:31]
	ds_read2_b64 v[76:79], v97 offset0:136 offset1:138
	s_addc_u32 s5, s17, s5
	s_lshl_b32 s6, s6, 1
	s_add_u32 s4, s4, s6
	s_addc_u32 s5, s5, 0
	v_mov_b32_e32 v175, v171
	s_waitcnt lgkmcnt(1)
	v_mfma_f32_32x32x16_bf16 v[0:15], v[72:75], v[86:89], v[0:15]
	v_exp_f32_e32 v86, v81
	v_cvt_pk_bf16_f32 v72, v94, v95
	v_cvt_pk_bf16_f32 v73, v98, v99
	v_cvt_pk_bf16_f32 v74, v84, v85
	v_cvt_pk_bf16_f32 v75, v100, v86
	ds_read2_b64 v[80:83], v170 offset0:168 offset1:170
	v_exp_f32_e32 v87, v66
	s_waitcnt lgkmcnt(1)
	v_mfma_f32_32x32x16_bf16 v[48:63], v[76:79], v[72:75], v[48:63]
	ds_read2_b64 v[76:79], v208 offset0:200 offset1:202
	v_exp_f32_e32 v88, v67
	ds_read2_b64 v[64:67], v209 offset0:232 offset1:234
	v_exp_f32_e32 v89, v70
	v_cvt_pk_bf16_f32 v68, v87, v88
	s_waitcnt lgkmcnt(1)
	v_mfma_f32_32x32x16_bf16 v[16:31], v[76:79], v[72:75], v[16:31]
	ds_read2_b64 v[76:79], v97 offset0:140 offset1:142
	v_cvt_pk_bf16_f32 v69, v89, v101
	v_cvt_pk_bf16_f32 v70, v102, v103
	s_add_i32 s34, s34, s86
	s_add_i32 s18, s18, s19
	s_cmpk_lt_i32 s34, 0x100
	s_waitcnt lgkmcnt(0)
	v_mfma_f32_32x32x16_bf16 v[48:63], v[76:79], v[68:71], v[48:63]
	v_add_f32_e32 v76, v105, v96
	v_add_f32_e32 v76, v106, v76
	v_add_f32_e32 v76, v107, v76
	v_add_f32_e32 v76, v109, v76
	v_add_f32_e32 v76, v110, v76
	v_add_f32_e32 v76, v111, v76
	v_add_f32_e32 v76, v112, v76
	v_mfma_f32_32x32x16_bf16 v[32:47], v[80:83], v[72:75], v[32:47]
	ds_read2_b64 v[80:83], v170 offset0:172 offset1:174
	v_add_f32_e32 v76, v90, v76
	v_add_f32_e32 v76, v91, v76
	v_add_f32_e32 v76, v113, v76
	v_add_f32_e32 v76, v114, v76
	v_add_f32_e32 v76, v115, v76
	v_mfma_f32_32x32x16_bf16 v[0:15], v[64:67], v[72:75], v[0:15]
	ds_read2_b64 v[64:67], v208 offset0:204 offset1:206
	v_add_f32_e32 v76, v92, v76
	v_add_f32_e32 v76, v93, v76
	ds_read2_b64 v[72:75], v209 offset0:236 offset1:238
	s_waitcnt lgkmcnt(0)
	v_mfma_f32_32x32x16_bf16 v[16:31], v[64:67], v[68:71], v[16:31]
	v_add_f32_e32 v64, v94, v76
	v_add_f32_e32 v64, v95, v64
	v_add_f32_e32 v64, v98, v64
	v_add_f32_e32 v64, v99, v64
	v_add_f32_e32 v64, v84, v64
	v_add_f32_e32 v64, v85, v64
	v_add_f32_e32 v64, v100, v64
	v_add_f32_e32 v64, v86, v64
	v_add_f32_e32 v64, v87, v64
	v_add_f32_e32 v64, v88, v64
	v_add_f32_e32 v64, v89, v64
	v_add_f32_e32 v64, v101, v64
	v_add_f32_e32 v64, v102, v64
	v_add_f32_e32 v64, v103, v64
	v_add_f32_e32 v64, v116, v64
	v_add_f32_e32 v64, v117, v64
	v_add_f32_e32 v64, v108, v64
	v_mov_b32_e32 v65, v64
	s_nop 1
	v_permlane32_swap_b32_e32 v64, v65
	v_add_f32_e32 v64, v64, v65
	v_div_scale_f32 v65, s[6:7], v64, v64, 1.0
	v_rcp_f32_e32 v66, v65
	v_mfma_f32_32x32x16_bf16 v[32:47], v[80:83], v[68:71], v[32:47]
	s_barrier
; DI unsigned pk2(float lo, float hi) { typedef float v2f __attribute__((ext_vector_type(2))); typedef __bf16 v2b __attribute__((ext_vector_type(2))); v2f v = {lo, hi}; v2b b = __builtin_convertvector(v, v2b); return __builtin_bit_cast(unsigned, b); }
; DI float xhalf_sum(float m) { auto rr = __builtin_amdgcn_permlane32_swap(__float_as_uint(m), __float_as_uint(m), false, false); return __uint_as_float(rr[0]) + __uint_as_float(rr[1]); }
; template <int DQK, int DV, bool CAUSAL, int KT, bool PRIO>
; DI void attn_unit(const bf16_t* Qb, int qpitch, const bf16_t* Kb, int kpitch, const bf16_t* Vtb, int vpitch, bf16_t* Ob, int opitch, int q0, int nt, LAS unsigned char* lds, float kbound, const float* qgain, const int* qpos, float qscale) {
;     ...
;     lrun = xhalf_sum(lrun);
;     const float inv = 1.0f / lrun;
;     bf16_t* orow = Ob + (size_t)(32 * w + r) * opitch;
; #pragma unroll
;     for (int d = 0; d < DV / 32; ++d)
; #pragma unroll
;         for (int g = 0; g < 4; ++g) { u32x2 wv; wv.x = pk2(o[d][4 * g] * inv, o[d][4 * g + 1] * inv); wv.y = pk2(o[d][4 * g + 2] * inv, o[d][4 * g + 3] * inv);
;             *(u32x2*)(orow + 32 * d + 8 * g + 4 * h) = wv; }
	v_fma_f32 v67, -v65, v66, 1.0
	v_fmac_f32_e32 v66, v67, v66
	v_div_scale_f32 v67, vcc, 1.0, v64, 1.0
	v_mfma_f32_32x32x16_bf16 v[0:15], v[72:75], v[68:71], v[0:15]
	v_mul_f32_e32 v68, v67, v66
	v_fma_f32 v69, -v65, v68, v67
	v_fmac_f32_e32 v68, v69, v66
	v_fma_f32 v65, -v65, v68, v67
	v_div_fmas_f32 v65, v65, v66, v68
	v_div_fixup_f32 v64, v65, v64, 1.0
	v_lshl_add_u64 v[66:67], s[4:5], 0, v[172:173]
	v_lshl_add_u64 v[66:67], v[174:175], 1, v[66:67]
	v_pk_mul_f32 v[48:49], v[48:49], v[64:65] op_sel_hi:[1,0]
	v_pk_mul_f32 v[50:51], v[50:51], v[64:65] op_sel_hi:[1,0]
	v_cvt_pk_bf16_f32 v48, v48, v49
	v_cvt_pk_bf16_f32 v49, v50, v51
	v_pk_mul_f32 v[52:53], v[52:53], v[64:65] op_sel_hi:[1,0]
	v_pk_mul_f32 v[54:55], v[54:55], v[64:65] op_sel_hi:[1,0]
	v_cvt_pk_bf16_f32 v50, v52, v53
	v_cvt_pk_bf16_f32 v51, v54, v55
	s_nop 1
	v_permlane32_swap_b32_e32 v48, v50
	v_permlane32_swap_b32_e32 v49, v51
	flat_store_dwordx4 v[66:67], v[48:51]
	v_pk_mul_f32 v[56:57], v[56:57], v[64:65] op_sel_hi:[1,0]
	v_pk_mul_f32 v[58:59], v[58:59], v[64:65] op_sel_hi:[1,0]
	v_cvt_pk_bf16_f32 v56, v56, v57
	v_cvt_pk_bf16_f32 v57, v58, v59
	v_pk_mul_f32 v[60:61], v[60:61], v[64:65] op_sel_hi:[1,0]
	v_pk_mul_f32 v[62:63], v[62:63], v[64:65] op_sel_hi:[1,0]
	v_cvt_pk_bf16_f32 v58, v60, v61
	v_cvt_pk_bf16_f32 v59, v62, v63
	s_nop 1
	v_permlane32_swap_b32_e32 v56, v58
	v_permlane32_swap_b32_e32 v57, v59
	flat_store_dwordx4 v[66:67], v[56:59] offset:32
	v_pk_mul_f32 v[32:33], v[32:33], v[64:65] op_sel_hi:[1,0]
	v_pk_mul_f32 v[34:35], v[34:35], v[64:65] op_sel_hi:[1,0]
	v_cvt_pk_bf16_f32 v32, v32, v33
	v_cvt_pk_bf16_f32 v33, v34, v35
	v_pk_mul_f32 v[36:37], v[36:37], v[64:65] op_sel_hi:[1,0]
	v_pk_mul_f32 v[38:39], v[38:39], v[64:65] op_sel_hi:[1,0]
	v_cvt_pk_bf16_f32 v34, v36, v37
	v_cvt_pk_bf16_f32 v35, v38, v39
	s_nop 1
	v_permlane32_swap_b32_e32 v32, v34
	v_permlane32_swap_b32_e32 v33, v35
	flat_store_dwordx4 v[66:67], v[32:35] offset:64
	v_pk_mul_f32 v[40:41], v[40:41], v[64:65] op_sel_hi:[1,0]
	v_pk_mul_f32 v[42:43], v[42:43], v[64:65] op_sel_hi:[1,0]
	v_cvt_pk_bf16_f32 v40, v40, v41
	v_cvt_pk_bf16_f32 v41, v42, v43
	v_pk_mul_f32 v[44:45], v[44:45], v[64:65] op_sel_hi:[1,0]
	v_pk_mul_f32 v[46:47], v[46:47], v[64:65] op_sel_hi:[1,0]
	v_cvt_pk_bf16_f32 v42, v44, v45
	v_cvt_pk_bf16_f32 v43, v46, v47
	s_nop 1
	v_permlane32_swap_b32_e32 v40, v42
	v_permlane32_swap_b32_e32 v41, v43
	flat_store_dwordx4 v[66:67], v[40:43] offset:96
	v_pk_mul_f32 v[16:17], v[16:17], v[64:65] op_sel_hi:[1,0]
	v_pk_mul_f32 v[18:19], v[18:19], v[64:65] op_sel_hi:[1,0]
	v_cvt_pk_bf16_f32 v16, v16, v17
	v_cvt_pk_bf16_f32 v17, v18, v19
	v_pk_mul_f32 v[20:21], v[20:21], v[64:65] op_sel_hi:[1,0]
	v_pk_mul_f32 v[22:23], v[22:23], v[64:65] op_sel_hi:[1,0]
	v_cvt_pk_bf16_f32 v18, v20, v21
	v_cvt_pk_bf16_f32 v19, v22, v23
	s_nop 1
	v_permlane32_swap_b32_e32 v16, v18
	v_permlane32_swap_b32_e32 v17, v19
	flat_store_dwordx4 v[66:67], v[16:19] offset:128
	v_pk_mul_f32 v[24:25], v[24:25], v[64:65] op_sel_hi:[1,0]
	v_pk_mul_f32 v[26:27], v[26:27], v[64:65] op_sel_hi:[1,0]
	v_cvt_pk_bf16_f32 v24, v24, v25
	v_cvt_pk_bf16_f32 v25, v26, v27
	v_pk_mul_f32 v[28:29], v[28:29], v[64:65] op_sel_hi:[1,0]
	v_pk_mul_f32 v[30:31], v[30:31], v[64:65] op_sel_hi:[1,0]
	v_cvt_pk_bf16_f32 v26, v28, v29
	v_cvt_pk_bf16_f32 v27, v30, v31
	s_nop 1
	v_permlane32_swap_b32_e32 v24, v26
	v_permlane32_swap_b32_e32 v25, v27
	flat_store_dwordx4 v[66:67], v[24:27] offset:160
	v_pk_mul_f32 v[0:1], v[0:1], v[64:65] op_sel_hi:[1,0]
	v_pk_mul_f32 v[2:3], v[2:3], v[64:65] op_sel_hi:[1,0]
	v_cvt_pk_bf16_f32 v0, v0, v1
	v_cvt_pk_bf16_f32 v1, v2, v3
	v_pk_mul_f32 v[4:5], v[4:5], v[64:65] op_sel_hi:[1,0]
	v_pk_mul_f32 v[6:7], v[6:7], v[64:65] op_sel_hi:[1,0]
	v_cvt_pk_bf16_f32 v2, v4, v5
	v_cvt_pk_bf16_f32 v3, v6, v7
	s_nop 1
	v_permlane32_swap_b32_e32 v0, v2
	v_permlane32_swap_b32_e32 v1, v3
	flat_store_dwordx4 v[66:67], v[0:3] offset:192
	v_pk_mul_f32 v[8:9], v[8:9], v[64:65] op_sel_hi:[1,0]
	v_pk_mul_f32 v[10:11], v[10:11], v[64:65] op_sel_hi:[1,0]
	v_cvt_pk_bf16_f32 v8, v8, v9
	v_cvt_pk_bf16_f32 v9, v10, v11
	v_pk_mul_f32 v[12:13], v[12:13], v[64:65] op_sel_hi:[1,0]
	v_pk_mul_f32 v[14:15], v[14:15], v[64:65] op_sel_hi:[1,0]
	v_cvt_pk_bf16_f32 v10, v12, v13
	v_cvt_pk_bf16_f32 v11, v14, v15
	s_nop 1
	v_permlane32_swap_b32_e32 v8, v10
	v_permlane32_swap_b32_e32 v9, v11
	flat_store_dwordx4 v[66:67], v[8:11] offset:224
	s_cbranch_scc0 .LBB0_1531
